# conv tr_item: the 16 per-row scale loads of each scaled 64x64 item issued together behind the tile loads (one wait) instead of 16 serialized load-wait round trips
# baseline (speedup 1.0000x reference)
; DI void tr_item(const float* W, int N, const float* scale, bf16_t* WT, int ldk, int koff, int gu, int which, float* scr, int item, int lane) {
;     const int nblk = N >> 6, kb = item / nblk, nb = item - kb * nblk, k0 = 64 * kb, n0 = 64 * nb;
;     const int lr = lane >> 4, lc = (lane & 15) * 4;
;     f32x4 v[16];
; #pragma unroll
;     for (int i = 0; i < 16; ++i) v[i] = *(const f32x4*)(W + (size_t)(k0 + 4 * i + lr) * N + n0 + lc);
; #pragma unroll
;     for (int i = 0; i < 16; ++i) { const int kk = 4 * i + lr; const float sc = scale ? scale[k0 + kk] : 1.f; float* d = scr + kk * 65 + lc;
;         d[0] = v[i].x * sc; d[1] = v[i].y * sc; d[2] = v[i].z * sc; d[3] = v[i].w * sc; }
.LBB0_393:
	s_andn2_saveexec_b64 s[28:29], s[28:29]
	s_cbranch_execz .LBB0_419
	s_load_dwordx2 s[4:5], s[0:1], 0xd0
	v_add_u32_e32 v0, 0xb00, v113
	v_mul_u32_u24_e32 v2, 0xba2f, v0
	v_lshrrev_b32_e32 v2, 22, v2
	s_movk_i32 s6, 0xffa8
	v_mad_i32_i24 v91, v2, s6, v0
	s_waitcnt lgkmcnt(0)
	s_add_u32 s4, s4, s43
	v_lshlrev_b32_e32 v88, 6, v91
	s_addc_u32 s5, s5, s20
	v_lshlrev_b32_e32 v90, 6, v2
	v_ashrrev_i32_e32 v89, 31, v88
	v_or_b32_e32 v158, v90, v70
	v_lshl_add_u64 v[2:3], v[88:89], 2, s[4:5]
	v_lshlrev_b32_e32 v0, 2, v72
	v_lshl_add_u64 v[2:3], v[2:3], 0, v[0:1]
	s_movk_i32 s4, 0x5800
	v_mul_u32_u24_e32 v0, 0x1600, v158
	v_mad_u64_u32 v[4:5], s[4:5], v158, s4, v[2:3]
	v_lshlrev_b32_e32 v0, 2, v0
	v_lshl_add_u64 v[2:3], v[2:3], 0, v[0:1]
	s_mov_b32 s4, 0x16000
	v_add_co_u32_e32 v6, vcc, s4, v2
	s_mov_b32 s4, 0x2c000
	s_nop 0
	v_addc_co_u32_e32 v7, vcc, 0, v3, vcc
	global_load_dwordx4 v[62:65], v[4:5], off
	global_load_dwordx4 v[58:61], v[6:7], off
	v_add_co_u32_e32 v4, vcc, s4, v2
	s_mov_b32 s4, 0x42000
	s_nop 0
	v_addc_co_u32_e32 v5, vcc, 0, v3, vcc
	v_add_co_u32_e32 v6, vcc, s4, v2
	s_mov_b32 s4, 0x58000
	s_nop 0
	v_addc_co_u32_e32 v7, vcc, 0, v3, vcc
	global_load_dwordx4 v[54:57], v[4:5], off
	global_load_dwordx4 v[50:53], v[6:7], off
	v_add_co_u32_e32 v4, vcc, s4, v2
	s_mov_b32 s4, 0x6e000
	s_nop 0
	v_addc_co_u32_e32 v5, vcc, 0, v3, vcc
	v_add_co_u32_e32 v6, vcc, s4, v2
	s_mov_b32 s4, 0x84000
	s_nop 0
	v_addc_co_u32_e32 v7, vcc, 0, v3, vcc
	global_load_dwordx4 v[46:49], v[4:5], off
	global_load_dwordx4 v[42:45], v[6:7], off
	v_add_co_u32_e32 v4, vcc, s4, v2
	s_mov_b32 s4, 0x9a000
	s_nop 0
	v_addc_co_u32_e32 v5, vcc, 0, v3, vcc
	v_add_co_u32_e32 v6, vcc, s4, v2
	s_mov_b32 s4, 0xb0000
	s_nop 0
	v_addc_co_u32_e32 v7, vcc, 0, v3, vcc
	global_load_dwordx4 v[38:41], v[4:5], off
	global_load_dwordx4 v[34:37], v[6:7], off
	v_add_co_u32_e32 v4, vcc, s4, v2
	s_mov_b32 s4, 0xc6000
	s_nop 0
	v_addc_co_u32_e32 v5, vcc, 0, v3, vcc
	v_add_co_u32_e32 v6, vcc, s4, v2
	s_mov_b32 s4, 0xdc000
	s_nop 0
	v_addc_co_u32_e32 v7, vcc, 0, v3, vcc
	global_load_dwordx4 v[30:33], v[4:5], off
	global_load_dwordx4 v[26:29], v[6:7], off
	v_add_co_u32_e32 v4, vcc, s4, v2
	s_mov_b32 s4, 0xf2000
	s_nop 0
	v_addc_co_u32_e32 v5, vcc, 0, v3, vcc
	v_add_co_u32_e32 v6, vcc, s4, v2
	s_mov_b32 s4, 0x108000
	s_nop 0
	v_addc_co_u32_e32 v7, vcc, 0, v3, vcc
	global_load_dwordx4 v[22:25], v[4:5], off
	global_load_dwordx4 v[18:21], v[6:7], off
	v_add_co_u32_e32 v4, vcc, s4, v2
	v_cndmask_b32_e64 v0, 0, 1, s[52:53]
	s_nop 0
	v_addc_co_u32_e32 v5, vcc, 0, v3, vcc
	v_add_co_u32_e32 v6, vcc, 0x11e000, v2
	v_cmp_ne_u32_e64 s[40:41], 1, v0
	s_nop 0
	v_addc_co_u32_e32 v7, vcc, 0, v3, vcc
	global_load_dwordx4 v[14:17], v[4:5], off
	global_load_dwordx4 v[10:13], v[6:7], off
	v_add_co_u32_e32 v4, vcc, 0x134000, v2
	v_add_lshl_u32 v89, v90, v70, 2
	s_nop 0
	v_addc_co_u32_e32 v5, vcc, 0, v3, vcc
	v_add_co_u32_e32 v2, vcc, 0x14a000, v2
	s_nop 1
	v_addc_co_u32_e32 v3, vcc, 0, v3, vcc
	global_load_dwordx4 v[6:9], v[4:5], off
	s_nop 0
	global_load_dwordx4 v[2:5], v[2:3], off
	s_andn2_b64 vcc, exec, s[52:53]
	s_cbranch_vccnz .LBB0_499
	v_lshlrev_b32_e32 v0, 2, v158
	global_load_dword v0, v0, s[48:49]
	global_load_dword v218, v89, s[48:49] offset:16
	global_load_dword v219, v89, s[48:49] offset:32
	global_load_dword v220, v89, s[48:49] offset:48
	global_load_dword v221, v89, s[48:49] offset:64
	global_load_dword v222, v89, s[48:49] offset:80
	global_load_dword v223, v89, s[48:49] offset:96
	global_load_dword v224, v89, s[48:49] offset:112
	global_load_dword v225, v89, s[48:49] offset:128
	global_load_dword v226, v89, s[48:49] offset:144
	global_load_dword v227, v89, s[48:49] offset:160
	global_load_dword v228, v89, s[48:49] offset:176
	global_load_dword v229, v89, s[48:49] offset:192
	global_load_dword v230, v89, s[48:49] offset:208
	global_load_dword v231, v89, s[48:49] offset:224
	global_load_dword v232, v89, s[48:49] offset:240
	s_waitcnt vmcnt(0)
	v_pk_mul_f32 v[158:159], v[62:63], v[0:1] op_sel_hi:[1,0]
	ds_write2_b32 v73, v158, v159 offset1:1
	v_pk_mul_f32 v[158:159], v[64:65], v[0:1] op_sel_hi:[1,0]
	v_mov_b32_e32 v0, v218
	ds_write2_b32 v73, v158, v159 offset0:2 offset1:3
	s_cbranch_execnz .LBB0_397

; DI void tr_item(const float* W, int N, const float* scale, bf16_t* WT, int ldk, int koff, int gu, int which, float* scr, int item, int lane) {
;     ...
;     for (int i = 0; i < 16; ++i) { const int kk = 4 * i + lr; const float sc = scale ? scale[k0 + kk] : 1.f; float* d = scr + kk * 65 + lc;
;         d[0] = v[i].x * sc; d[1] = v[i].y * sc; d[2] = v[i].z * sc; d[3] = v[i].w * sc; }
.LBB0_397:
	s_waitcnt vmcnt(0)
	v_pk_mul_f32 v[58:59], v[58:59], v[0:1] op_sel_hi:[1,0]
	v_add_u32_e32 v62, v69, v101
	ds_write2_b32 v62, v58, v59 offset1:1
	v_pk_mul_f32 v[58:59], v[60:61], v[0:1] op_sel_hi:[1,0]
	s_and_b64 vcc, exec, s[40:41]
	ds_write2_b32 v62, v58, v59 offset0:2 offset1:3
	s_cbranch_vccnz .LBB0_500
	v_mov_b32_e32 v0, v219
	v_add_u32_e32 v60, v69, v102
	s_waitcnt vmcnt(0)
	v_pk_mul_f32 v[58:59], v[54:55], v[0:1] op_sel_hi:[1,0]
	ds_write2_b32 v60, v58, v59 offset1:1
	v_pk_mul_f32 v[58:59], v[56:57], v[0:1] op_sel_hi:[1,0]
	v_mov_b32_e32 v0, v220
	ds_write2_b32 v60, v58, v59 offset0:2 offset1:3
	s_cbranch_execnz .LBB0_400

; DI void tr_item(const float* W, int N, const float* scale, bf16_t* WT, int ldk, int koff, int gu, int which, float* scr, int item, int lane) {
;     ...
;     for (int i = 0; i < 16; ++i) { const int kk = 4 * i + lr; const float sc = scale ? scale[k0 + kk] : 1.f; float* d = scr + kk * 65 + lc;
;         d[0] = v[i].x * sc; d[1] = v[i].y * sc; d[2] = v[i].z * sc; d[3] = v[i].w * sc; }
.LBB0_400:
	s_waitcnt vmcnt(0)
	v_pk_mul_f32 v[50:51], v[50:51], v[0:1] op_sel_hi:[1,0]
	v_add_u32_e32 v54, v69, v103
	ds_write2_b32 v54, v50, v51 offset1:1
	v_pk_mul_f32 v[50:51], v[52:53], v[0:1] op_sel_hi:[1,0]
	s_and_b64 vcc, exec, s[40:41]
	ds_write2_b32 v54, v50, v51 offset0:2 offset1:3
	s_cbranch_vccnz .LBB0_501
	v_mov_b32_e32 v0, v221
	v_add_u32_e32 v52, v69, v104
	s_waitcnt vmcnt(0)
	v_pk_mul_f32 v[50:51], v[46:47], v[0:1] op_sel_hi:[1,0]
	ds_write2_b32 v52, v50, v51 offset1:1
	v_pk_mul_f32 v[50:51], v[48:49], v[0:1] op_sel_hi:[1,0]
	v_mov_b32_e32 v0, v222
	ds_write2_b32 v52, v50, v51 offset0:2 offset1:3
	s_cbranch_execnz .LBB0_403

; DI void tr_item(const float* W, int N, const float* scale, bf16_t* WT, int ldk, int koff, int gu, int which, float* scr, int item, int lane) {
;     ...
;     for (int i = 0; i < 16; ++i) { const int kk = 4 * i + lr; const float sc = scale ? scale[k0 + kk] : 1.f; float* d = scr + kk * 65 + lc;
;         d[0] = v[i].x * sc; d[1] = v[i].y * sc; d[2] = v[i].z * sc; d[3] = v[i].w * sc; }
.LBB0_403:
	s_waitcnt vmcnt(0)
	v_pk_mul_f32 v[42:43], v[42:43], v[0:1] op_sel_hi:[1,0]
	v_add_u32_e32 v46, v69, v105
	ds_write2_b32 v46, v42, v43 offset1:1
	v_pk_mul_f32 v[42:43], v[44:45], v[0:1] op_sel_hi:[1,0]
	s_and_b64 vcc, exec, s[40:41]
	ds_write2_b32 v46, v42, v43 offset0:2 offset1:3
	s_cbranch_vccnz .LBB0_502
	v_mov_b32_e32 v0, v223
	v_add_u32_e32 v44, v69, v106
	s_waitcnt vmcnt(0)
	v_pk_mul_f32 v[42:43], v[38:39], v[0:1] op_sel_hi:[1,0]
	ds_write2_b32 v44, v42, v43 offset1:1
	v_pk_mul_f32 v[42:43], v[40:41], v[0:1] op_sel_hi:[1,0]
	v_mov_b32_e32 v0, v224
	ds_write2_b32 v44, v42, v43 offset0:2 offset1:3
	s_cbranch_execnz .LBB0_406

; DI void tr_item(const float* W, int N, const float* scale, bf16_t* WT, int ldk, int koff, int gu, int which, float* scr, int item, int lane) {
;     ...
;     for (int i = 0; i < 16; ++i) { const int kk = 4 * i + lr; const float sc = scale ? scale[k0 + kk] : 1.f; float* d = scr + kk * 65 + lc;
;         d[0] = v[i].x * sc; d[1] = v[i].y * sc; d[2] = v[i].z * sc; d[3] = v[i].w * sc; }
.LBB0_406:
	s_waitcnt vmcnt(0)
	v_pk_mul_f32 v[34:35], v[34:35], v[0:1] op_sel_hi:[1,0]
	v_add_u32_e32 v38, v69, v107
	ds_write2_b32 v38, v34, v35 offset1:1
	v_pk_mul_f32 v[34:35], v[36:37], v[0:1] op_sel_hi:[1,0]
	s_and_b64 vcc, exec, s[40:41]
	ds_write2_b32 v38, v34, v35 offset0:2 offset1:3
	s_cbranch_vccnz .LBB0_503
	v_mov_b32_e32 v0, v225
	v_add_u32_e32 v36, v69, v108
	s_waitcnt vmcnt(0)
	v_pk_mul_f32 v[34:35], v[30:31], v[0:1] op_sel_hi:[1,0]
	ds_write2_b32 v36, v34, v35 offset1:1
	v_pk_mul_f32 v[34:35], v[32:33], v[0:1] op_sel_hi:[1,0]
	v_mov_b32_e32 v0, v226
	ds_write2_b32 v36, v34, v35 offset0:2 offset1:3
	s_cbranch_execnz .LBB0_409

; DI void tr_item(const float* W, int N, const float* scale, bf16_t* WT, int ldk, int koff, int gu, int which, float* scr, int item, int lane) {
;     ...
;     for (int i = 0; i < 16; ++i) { const int kk = 4 * i + lr; const float sc = scale ? scale[k0 + kk] : 1.f; float* d = scr + kk * 65 + lc;
;         d[0] = v[i].x * sc; d[1] = v[i].y * sc; d[2] = v[i].z * sc; d[3] = v[i].w * sc; }
.LBB0_409:
	s_waitcnt vmcnt(0)
	v_pk_mul_f32 v[26:27], v[26:27], v[0:1] op_sel_hi:[1,0]
	v_add_u32_e32 v30, v69, v109
	ds_write2_b32 v30, v26, v27 offset1:1
	v_pk_mul_f32 v[26:27], v[28:29], v[0:1] op_sel_hi:[1,0]
	s_and_b64 vcc, exec, s[40:41]
	ds_write2_b32 v30, v26, v27 offset0:2 offset1:3
	s_cbranch_vccnz .LBB0_504
	v_mov_b32_e32 v0, v227
	v_add_u32_e32 v28, v69, v110
	s_waitcnt vmcnt(0)
	v_pk_mul_f32 v[26:27], v[22:23], v[0:1] op_sel_hi:[1,0]
	ds_write2_b32 v28, v26, v27 offset1:1
	v_pk_mul_f32 v[26:27], v[24:25], v[0:1] op_sel_hi:[1,0]
	v_mov_b32_e32 v0, v228
	ds_write2_b32 v28, v26, v27 offset0:2 offset1:3
	s_cbranch_execnz .LBB0_412

; DI void tr_item(const float* W, int N, const float* scale, bf16_t* WT, int ldk, int koff, int gu, int which, float* scr, int item, int lane) {
;     ...
;     for (int i = 0; i < 16; ++i) { const int kk = 4 * i + lr; const float sc = scale ? scale[k0 + kk] : 1.f; float* d = scr + kk * 65 + lc;
;         d[0] = v[i].x * sc; d[1] = v[i].y * sc; d[2] = v[i].z * sc; d[3] = v[i].w * sc; }
.LBB0_412:
	s_waitcnt vmcnt(0)
	v_pk_mul_f32 v[22:23], v[18:19], v[0:1] op_sel_hi:[1,0]
	v_add_u32_e32 v18, v69, v111
	v_pk_mul_f32 v[20:21], v[20:21], v[0:1] op_sel_hi:[1,0]
	ds_write2_b32 v18, v20, v21 offset0:2 offset1:3
	s_and_b64 vcc, exec, s[40:41]
	v_add_u32_e32 v19, 0x410, v18
	v_add_u32_e32 v20, 0x418, v18
	ds_write2_b32 v18, v22, v23 offset1:1
	s_cbranch_vccnz .LBB0_505
	v_mov_b32_e32 v0, v229
	s_waitcnt vmcnt(0)
	v_pk_mul_f32 v[22:23], v[14:15], v[0:1] op_sel_hi:[1,0]
	ds_write2_b32 v19, v22, v23 offset1:1
	v_pk_mul_f32 v[22:23], v[16:17], v[0:1] op_sel_hi:[1,0]
	v_mov_b32_e32 v0, v230
	ds_write2_b32 v20, v22, v23 offset1:1
	s_cbranch_execnz .LBB0_415

; DI void tr_item(const float* W, int N, const float* scale, bf16_t* WT, int ldk, int koff, int gu, int which, float* scr, int item, int lane) {
;     ...
;     for (int i = 0; i < 16; ++i) { const int kk = 4 * i + lr; const float sc = scale ? scale[k0 + kk] : 1.f; float* d = scr + kk * 65 + lc;
;         d[0] = v[i].x * sc; d[1] = v[i].y * sc; d[2] = v[i].z * sc; d[3] = v[i].w * sc; }
.LBB0_415:
	s_waitcnt vmcnt(0)
	v_pk_mul_f32 v[10:11], v[10:11], v[0:1] op_sel_hi:[1,0]
	v_add_u32_e32 v14, 0x820, v18
	ds_write2_b32 v14, v10, v11 offset1:1
	v_pk_mul_f32 v[10:11], v[12:13], v[0:1] op_sel_hi:[1,0]
	v_add_u32_e32 v0, 0x828, v18
	ds_write2_b32 v0, v10, v11 offset1:1
	s_and_b64 vcc, exec, s[40:41]
	v_add_u32_e32 v10, 0xc30, v18
	v_add_u32_e32 v11, 0xc38, v18
	s_cbranch_vccnz .LBB0_506
	v_mov_b32_e32 v0, v231
	s_waitcnt vmcnt(0)
	v_pk_mul_f32 v[12:13], v[6:7], v[0:1] op_sel_hi:[1,0]
	ds_write2_b32 v10, v12, v13 offset1:1
	v_pk_mul_f32 v[12:13], v[8:9], v[0:1] op_sel_hi:[1,0]
	v_mov_b32_e32 v0, v232
	ds_write2_b32 v11, v12, v13 offset1:1
	s_cbranch_execnz .LBB0_418

; DI void tr_item(const float* W, int N, const float* scale, bf16_t* WT, int ldk, int koff, int gu, int which, float* scr, int item, int lane) {
;     const int nblk = N >> 6, kb = item / nblk, nb = item - kb * nblk, k0 = 64 * kb, n0 = 64 * nb;
;     const int lr = lane >> 4, lc = (lane & 15) * 4;
;     f32x4 v[16];
; #pragma unroll
;     for (int i = 0; i < 16; ++i) v[i] = *(const f32x4*)(W + (size_t)(k0 + 4 * i + lr) * N + n0 + lc);
; #pragma unroll
;     for (int i = 0; i < 16; ++i) { const int kk = 4 * i + lr; const float sc = scale ? scale[k0 + kk] : 1.f; float* d = scr + kk * 65 + lc;
;         d[0] = v[i].x * sc; d[1] = v[i].y * sc; d[2] = v[i].z * sc; d[3] = v[i].w * sc; }
.LBB0_420:
	s_andn2_saveexec_b64 s[38:39], s[38:39]
	s_cbranch_execz .LBB0_446
	s_load_dwordx2 s[4:5], s[0:1], 0xc8
	v_add_u32_e32 v0, 0x1600, v113
	v_mul_u32_u24_e32 v2, 0xba2f, v0
	v_lshrrev_b32_e32 v2, 22, v2
	s_movk_i32 s6, 0xffa8
	v_mad_i32_i24 v91, v2, s6, v0
	s_waitcnt lgkmcnt(0)
	s_add_u32 s4, s4, s43
	v_lshlrev_b32_e32 v88, 6, v91
	s_addc_u32 s5, s5, s20
	v_lshlrev_b32_e32 v90, 6, v2
	v_ashrrev_i32_e32 v89, 31, v88
	v_or_b32_e32 v158, v90, v70
	v_lshl_add_u64 v[2:3], v[88:89], 2, s[4:5]
	v_lshlrev_b32_e32 v0, 2, v72
	v_lshl_add_u64 v[2:3], v[2:3], 0, v[0:1]
	s_movk_i32 s4, 0x5800
	v_mul_u32_u24_e32 v0, 0x1600, v158
	v_mad_u64_u32 v[4:5], s[4:5], v158, s4, v[2:3]
	v_lshlrev_b32_e32 v0, 2, v0
	v_lshl_add_u64 v[2:3], v[2:3], 0, v[0:1]
	s_mov_b32 s4, 0x16000
	v_add_co_u32_e32 v6, vcc, s4, v2
	s_mov_b32 s4, 0x2c000
	s_nop 0
	v_addc_co_u32_e32 v7, vcc, 0, v3, vcc
	global_load_dwordx4 v[62:65], v[4:5], off
	global_load_dwordx4 v[58:61], v[6:7], off
	v_add_co_u32_e32 v4, vcc, s4, v2
	s_mov_b32 s4, 0x42000
	s_nop 0
	v_addc_co_u32_e32 v5, vcc, 0, v3, vcc
	v_add_co_u32_e32 v6, vcc, s4, v2
	s_mov_b32 s4, 0x58000
	s_nop 0
	v_addc_co_u32_e32 v7, vcc, 0, v3, vcc
	global_load_dwordx4 v[54:57], v[4:5], off
	global_load_dwordx4 v[50:53], v[6:7], off
	v_add_co_u32_e32 v4, vcc, s4, v2
	s_mov_b32 s4, 0x6e000
	s_nop 0
	v_addc_co_u32_e32 v5, vcc, 0, v3, vcc
	v_add_co_u32_e32 v6, vcc, s4, v2
	s_mov_b32 s4, 0x84000
	s_nop 0
	v_addc_co_u32_e32 v7, vcc, 0, v3, vcc
	global_load_dwordx4 v[46:49], v[4:5], off
	global_load_dwordx4 v[42:45], v[6:7], off
	v_add_co_u32_e32 v4, vcc, s4, v2
	s_mov_b32 s4, 0x9a000
	s_nop 0
	v_addc_co_u32_e32 v5, vcc, 0, v3, vcc
	v_add_co_u32_e32 v6, vcc, s4, v2
	s_mov_b32 s4, 0xb0000
	s_nop 0
	v_addc_co_u32_e32 v7, vcc, 0, v3, vcc
	global_load_dwordx4 v[38:41], v[4:5], off
	global_load_dwordx4 v[34:37], v[6:7], off
	v_add_co_u32_e32 v4, vcc, s4, v2
	s_mov_b32 s4, 0xc6000
	s_nop 0
	v_addc_co_u32_e32 v5, vcc, 0, v3, vcc
	v_add_co_u32_e32 v6, vcc, s4, v2
	s_mov_b32 s4, 0xdc000
	s_nop 0
	v_addc_co_u32_e32 v7, vcc, 0, v3, vcc
	global_load_dwordx4 v[30:33], v[4:5], off
	global_load_dwordx4 v[26:29], v[6:7], off
	v_add_co_u32_e32 v4, vcc, s4, v2
	s_mov_b32 s4, 0xf2000
	s_nop 0
	v_addc_co_u32_e32 v5, vcc, 0, v3, vcc
	v_add_co_u32_e32 v6, vcc, s4, v2
	s_mov_b32 s4, 0x108000
	s_nop 0
	v_addc_co_u32_e32 v7, vcc, 0, v3, vcc
	global_load_dwordx4 v[22:25], v[4:5], off
	global_load_dwordx4 v[18:21], v[6:7], off
	v_add_co_u32_e32 v4, vcc, s4, v2
	v_cndmask_b32_e64 v0, 0, 1, s[52:53]
	s_nop 0
	v_addc_co_u32_e32 v5, vcc, 0, v3, vcc
	v_add_co_u32_e32 v6, vcc, 0x11e000, v2
	v_cmp_ne_u32_e64 s[40:41], 1, v0
	s_nop 0
	v_addc_co_u32_e32 v7, vcc, 0, v3, vcc
	global_load_dwordx4 v[14:17], v[4:5], off
	global_load_dwordx4 v[10:13], v[6:7], off
	v_add_co_u32_e32 v4, vcc, 0x134000, v2
	v_add_lshl_u32 v89, v90, v70, 2
	s_nop 0
	v_addc_co_u32_e32 v5, vcc, 0, v3, vcc
	v_add_co_u32_e32 v2, vcc, 0x14a000, v2
	s_nop 1
	v_addc_co_u32_e32 v3, vcc, 0, v3, vcc
	global_load_dwordx4 v[6:9], v[4:5], off
	s_nop 0
	global_load_dwordx4 v[2:5], v[2:3], off
	s_andn2_b64 vcc, exec, s[52:53]
	s_cbranch_vccnz .LBB0_491
	v_lshlrev_b32_e32 v0, 2, v158
	global_load_dword v0, v0, s[48:49]
	global_load_dword v218, v89, s[48:49] offset:16
	global_load_dword v219, v89, s[48:49] offset:32
	global_load_dword v220, v89, s[48:49] offset:48
	global_load_dword v221, v89, s[48:49] offset:64
	global_load_dword v222, v89, s[48:49] offset:80
	global_load_dword v223, v89, s[48:49] offset:96
	global_load_dword v224, v89, s[48:49] offset:112
	global_load_dword v225, v89, s[48:49] offset:128
	global_load_dword v226, v89, s[48:49] offset:144
	global_load_dword v227, v89, s[48:49] offset:160
	global_load_dword v228, v89, s[48:49] offset:176
	global_load_dword v229, v89, s[48:49] offset:192
	global_load_dword v230, v89, s[48:49] offset:208
	global_load_dword v231, v89, s[48:49] offset:224
	global_load_dword v232, v89, s[48:49] offset:240
	s_waitcnt vmcnt(0)
	v_pk_mul_f32 v[158:159], v[62:63], v[0:1] op_sel_hi:[1,0]
	ds_write2_b32 v73, v158, v159 offset1:1
	v_pk_mul_f32 v[158:159], v[64:65], v[0:1] op_sel_hi:[1,0]
	v_mov_b32_e32 v0, v218
	ds_write2_b32 v73, v158, v159 offset0:2 offset1:3
	s_cbranch_execnz .LBB0_424

; DI void tr_item(const float* W, int N, const float* scale, bf16_t* WT, int ldk, int koff, int gu, int which, float* scr, int item, int lane) {
;     const int nblk = N >> 6, kb = item / nblk, nb = item - kb * nblk, k0 = 64 * kb, n0 = 64 * nb;
;     const int lr = lane >> 4, lc = (lane & 15) * 4;
;     f32x4 v[16];
; #pragma unroll
;     for (int i = 0; i < 16; ++i) v[i] = *(const f32x4*)(W + (size_t)(k0 + 4 * i + lr) * N + n0 + lc);
; #pragma unroll
;     for (int i = 0; i < 16; ++i) { const int kk = 4 * i + lr; const float sc = scale ? scale[k0 + kk] : 1.f; float* d = scr + kk * 65 + lc;
;         d[0] = v[i].x * sc; d[1] = v[i].y * sc; d[2] = v[i].z * sc; d[3] = v[i].w * sc; }
.LBB0_459:
	s_andn2_saveexec_b64 s[12:13], s[68:69]
	s_cbranch_execz .LBB0_384
	s_load_dwordx2 s[4:5], s[0:1], 0x10
	v_ashrrev_i32_e32 v2, 31, v0
	v_lshrrev_b32_e32 v2, 25, v2
	v_add_u32_e32 v0, v0, v2
	v_ashrrev_i32_e32 v0, 7, v0
	v_lshlrev_b32_e32 v88, 6, v0
	v_lshlrev_b32_e32 v158, 13, v0
	s_waitcnt lgkmcnt(0)
	s_add_u32 s4, s4, s64
	v_sub_u32_e32 v2, v114, v158
	v_or_b32_e32 v90, v88, v70
	s_addc_u32 s5, s5, s65
	v_ashrrev_i32_e32 v3, 31, v2
	v_or_b32_e32 v6, 4, v90
	v_lshl_add_u64 v[2:3], v[2:3], 2, s[4:5]
	v_lshlrev_b32_e32 v0, 2, v72
	v_ashrrev_i32_e32 v91, 31, v90
	v_ashrrev_i32_e32 v7, 31, v6
	v_lshl_add_u64 v[2:3], v[2:3], 0, v[0:1]
	v_lshlrev_b64 v[4:5], 15, v[90:91]
	v_lshlrev_b64 v[6:7], 15, v[6:7]
	v_lshl_add_u64 v[4:5], v[2:3], 0, v[4:5]
	v_lshl_add_u64 v[6:7], v[2:3], 0, v[6:7]
	global_load_dwordx4 v[62:65], v[4:5], off
	global_load_dwordx4 v[58:61], v[6:7], off
	v_or_b32_e32 v4, 8, v90
	v_or_b32_e32 v6, 12, v90
	v_ashrrev_i32_e32 v5, 31, v4
	v_ashrrev_i32_e32 v7, 31, v6
	v_lshlrev_b64 v[4:5], 15, v[4:5]
	v_lshlrev_b64 v[6:7], 15, v[6:7]
	v_lshl_add_u64 v[4:5], v[2:3], 0, v[4:5]
	v_lshl_add_u64 v[6:7], v[2:3], 0, v[6:7]
	global_load_dwordx4 v[54:57], v[4:5], off
	global_load_dwordx4 v[50:53], v[6:7], off
	v_or_b32_e32 v4, 16, v90
	v_or_b32_e32 v6, 20, v90
	v_ashrrev_i32_e32 v5, 31, v4
	v_ashrrev_i32_e32 v7, 31, v6
	v_lshlrev_b64 v[4:5], 15, v[4:5]
	v_lshlrev_b64 v[6:7], 15, v[6:7]
	v_lshl_add_u64 v[4:5], v[2:3], 0, v[4:5]
	v_lshl_add_u64 v[6:7], v[2:3], 0, v[6:7]
	global_load_dwordx4 v[46:49], v[4:5], off
	global_load_dwordx4 v[42:45], v[6:7], off
	v_or_b32_e32 v4, 24, v90
	v_or_b32_e32 v6, 28, v90
	v_ashrrev_i32_e32 v5, 31, v4
	v_ashrrev_i32_e32 v7, 31, v6
	v_lshlrev_b64 v[4:5], 15, v[4:5]
	v_lshlrev_b64 v[6:7], 15, v[6:7]
	v_lshl_add_u64 v[4:5], v[2:3], 0, v[4:5]
	v_lshl_add_u64 v[6:7], v[2:3], 0, v[6:7]
	global_load_dwordx4 v[38:41], v[4:5], off
	global_load_dwordx4 v[34:37], v[6:7], off
	v_or_b32_e32 v4, 32, v90
	v_or_b32_e32 v6, 36, v90
	v_ashrrev_i32_e32 v5, 31, v4
	v_ashrrev_i32_e32 v7, 31, v6
	v_lshlrev_b64 v[4:5], 15, v[4:5]
	v_lshlrev_b64 v[6:7], 15, v[6:7]
	v_lshl_add_u64 v[4:5], v[2:3], 0, v[4:5]
	v_lshl_add_u64 v[6:7], v[2:3], 0, v[6:7]
	global_load_dwordx4 v[30:33], v[4:5], off
	global_load_dwordx4 v[26:29], v[6:7], off
	v_or_b32_e32 v4, 40, v90
	v_or_b32_e32 v6, 44, v90
	v_ashrrev_i32_e32 v5, 31, v4
	v_ashrrev_i32_e32 v7, 31, v6
	v_lshlrev_b64 v[4:5], 15, v[4:5]
	v_lshlrev_b64 v[6:7], 15, v[6:7]
	v_lshl_add_u64 v[4:5], v[2:3], 0, v[4:5]
	v_lshl_add_u64 v[6:7], v[2:3], 0, v[6:7]
	global_load_dwordx4 v[22:25], v[4:5], off
	global_load_dwordx4 v[18:21], v[6:7], off
	v_or_b32_e32 v4, 48, v90
	v_or_b32_e32 v6, 52, v90
	v_ashrrev_i32_e32 v5, 31, v4
	v_ashrrev_i32_e32 v7, 31, v6
	v_lshlrev_b64 v[4:5], 15, v[4:5]
	v_lshlrev_b64 v[6:7], 15, v[6:7]
	v_lshl_add_u64 v[4:5], v[2:3], 0, v[4:5]
	v_lshl_add_u64 v[6:7], v[2:3], 0, v[6:7]
	global_load_dwordx4 v[14:17], v[4:5], off
	global_load_dwordx4 v[10:13], v[6:7], off
	v_or_b32_e32 v4, 56, v90
	v_or_b32_e32 v6, 60, v90
	v_ashrrev_i32_e32 v5, 31, v4
	v_ashrrev_i32_e32 v7, 31, v6
	v_lshlrev_b64 v[4:5], 15, v[4:5]
	v_lshlrev_b64 v[6:7], 15, v[6:7]
	v_lshl_add_u64 v[4:5], v[2:3], 0, v[4:5]
	v_lshl_add_u64 v[2:3], v[2:3], 0, v[6:7]
	global_load_dwordx4 v[6:9], v[4:5], off
	s_nop 0
	global_load_dwordx4 v[2:5], v[2:3], off
	v_cndmask_b32_e64 v0, 0, 1, s[66:67]
	v_cmp_ne_u32_e64 s[40:41], 1, v0
	s_andn2_b64 vcc, exec, s[66:67]
	v_ashrrev_i32_e32 v89, 31, v88
	s_cbranch_vccnz .LBB0_483
	v_lshl_add_u64 v[90:91], v[90:91], 2, s[46:47]
	global_load_dword v0, v[90:91], off
	v_lshl_add_u64 v[216:217], v[88:89], 0, v[70:71]
	v_lshl_add_u64 v[216:217], v[216:217], 2, s[46:47]
	global_load_dword v218, v[216:217], off offset:16
	global_load_dword v219, v[216:217], off offset:32
	global_load_dword v220, v[216:217], off offset:48
	global_load_dword v221, v[216:217], off offset:64
	global_load_dword v222, v[216:217], off offset:80
	global_load_dword v223, v[216:217], off offset:96
	global_load_dword v224, v[216:217], off offset:112
	global_load_dword v225, v[216:217], off offset:128
	global_load_dword v226, v[216:217], off offset:144
	global_load_dword v227, v[216:217], off offset:160
	global_load_dword v228, v[216:217], off offset:176
	global_load_dword v229, v[216:217], off offset:192
	global_load_dword v230, v[216:217], off offset:208
	global_load_dword v231, v[216:217], off offset:224
	global_load_dword v232, v[216:217], off offset:240
	s_waitcnt vmcnt(0)
	v_pk_mul_f32 v[90:91], v[62:63], v[0:1] op_sel_hi:[1,0]
	ds_write2_b32 v73, v90, v91 offset1:1
	v_pk_mul_f32 v[90:91], v[64:65], v[0:1] op_sel_hi:[1,0]
	ds_write2_b32 v73, v90, v91 offset0:2 offset1:3
	v_lshl_add_u64 v[90:91], v[88:89], 0, v[70:71]
	v_lshl_add_u64 v[90:91], v[90:91], 2, s[46:47]
	v_mov_b32_e32 v0, v218
	s_cbranch_execnz .LBB0_463

; DI void tr_item(const float* W, int N, const float* scale, bf16_t* WT, int ldk, int koff, int gu, int which, float* scr, int item, int lane) {
;     ...
;     for (int i = 0; i < 16; ++i) { const int kk = 4 * i + lr; const float sc = scale ? scale[k0 + kk] : 1.f; float* d = scr + kk * 65 + lc;
;         d[0] = v[i].x * sc; d[1] = v[i].y * sc; d[2] = v[i].z * sc; d[3] = v[i].w * sc; }
.LBB0_463:
	s_waitcnt vmcnt(0)
	v_pk_mul_f32 v[58:59], v[58:59], v[0:1] op_sel_hi:[1,0]
	v_add_u32_e32 v62, v69, v101
	ds_write2_b32 v62, v58, v59 offset1:1
	v_pk_mul_f32 v[58:59], v[60:61], v[0:1] op_sel_hi:[1,0]
	ds_write2_b32 v62, v58, v59 offset0:2 offset1:3
	s_and_b64 vcc, exec, s[40:41]
	v_add_u32_e32 v58, v69, v102
	s_cbranch_vccnz .LBB0_484
	v_lshl_add_u64 v[60:61], v[88:89], 0, v[70:71]
	v_lshl_add_u64 v[60:61], v[60:61], 2, s[46:47]
	v_mov_b32_e32 v0, v219
	s_waitcnt vmcnt(0)
	v_pk_mul_f32 v[62:63], v[54:55], v[0:1] op_sel_hi:[1,0]
	ds_write2_b32 v58, v62, v63 offset1:1
	v_pk_mul_f32 v[62:63], v[56:57], v[0:1] op_sel_hi:[1,0]
	v_mov_b32_e32 v0, v220
	ds_write2_b32 v58, v62, v63 offset0:2 offset1:3
	s_cbranch_execnz .LBB0_466

; DI void tr_item(const float* W, int N, const float* scale, bf16_t* WT, int ldk, int koff, int gu, int which, float* scr, int item, int lane) {
;     ...
;     for (int i = 0; i < 16; ++i) { const int kk = 4 * i + lr; const float sc = scale ? scale[k0 + kk] : 1.f; float* d = scr + kk * 65 + lc;
;         d[0] = v[i].x * sc; d[1] = v[i].y * sc; d[2] = v[i].z * sc; d[3] = v[i].w * sc; }
.LBB0_466:
	s_waitcnt vmcnt(0)
	v_pk_mul_f32 v[50:51], v[50:51], v[0:1] op_sel_hi:[1,0]
	v_add_u32_e32 v54, v69, v103
	ds_write2_b32 v54, v50, v51 offset1:1
	v_pk_mul_f32 v[50:51], v[52:53], v[0:1] op_sel_hi:[1,0]
	ds_write2_b32 v54, v50, v51 offset0:2 offset1:3
	s_and_b64 vcc, exec, s[40:41]
	v_add_u32_e32 v50, v69, v104
	s_cbranch_vccnz .LBB0_485
	v_lshl_add_u64 v[52:53], v[88:89], 0, v[70:71]
	v_lshl_add_u64 v[52:53], v[52:53], 2, s[46:47]
	v_mov_b32_e32 v0, v221
	s_waitcnt vmcnt(0)
	v_pk_mul_f32 v[54:55], v[46:47], v[0:1] op_sel_hi:[1,0]
	ds_write2_b32 v50, v54, v55 offset1:1
	v_pk_mul_f32 v[54:55], v[48:49], v[0:1] op_sel_hi:[1,0]
	v_mov_b32_e32 v0, v222
	ds_write2_b32 v50, v54, v55 offset0:2 offset1:3
	s_cbranch_execnz .LBB0_469

; DI void tr_item(const float* W, int N, const float* scale, bf16_t* WT, int ldk, int koff, int gu, int which, float* scr, int item, int lane) {
;     ...
;     for (int i = 0; i < 16; ++i) { const int kk = 4 * i + lr; const float sc = scale ? scale[k0 + kk] : 1.f; float* d = scr + kk * 65 + lc;
;         d[0] = v[i].x * sc; d[1] = v[i].y * sc; d[2] = v[i].z * sc; d[3] = v[i].w * sc; }
.LBB0_469:
	s_waitcnt vmcnt(0)
	v_pk_mul_f32 v[42:43], v[42:43], v[0:1] op_sel_hi:[1,0]
	v_add_u32_e32 v46, v69, v105
	ds_write2_b32 v46, v42, v43 offset1:1
	v_pk_mul_f32 v[42:43], v[44:45], v[0:1] op_sel_hi:[1,0]
	ds_write2_b32 v46, v42, v43 offset0:2 offset1:3
	s_and_b64 vcc, exec, s[40:41]
	v_add_u32_e32 v42, v69, v106
	s_cbranch_vccnz .LBB0_486
	v_lshl_add_u64 v[44:45], v[88:89], 0, v[70:71]
	v_lshl_add_u64 v[44:45], v[44:45], 2, s[46:47]
	v_mov_b32_e32 v0, v223
	s_waitcnt vmcnt(0)
	v_pk_mul_f32 v[46:47], v[38:39], v[0:1] op_sel_hi:[1,0]
	ds_write2_b32 v42, v46, v47 offset1:1
	v_pk_mul_f32 v[46:47], v[40:41], v[0:1] op_sel_hi:[1,0]
	v_mov_b32_e32 v0, v224
	ds_write2_b32 v42, v46, v47 offset0:2 offset1:3
	s_cbranch_execnz .LBB0_472

; DI void tr_item(const float* W, int N, const float* scale, bf16_t* WT, int ldk, int koff, int gu, int which, float* scr, int item, int lane) {
;     ...
;     for (int i = 0; i < 16; ++i) { const int kk = 4 * i + lr; const float sc = scale ? scale[k0 + kk] : 1.f; float* d = scr + kk * 65 + lc;
;         d[0] = v[i].x * sc; d[1] = v[i].y * sc; d[2] = v[i].z * sc; d[3] = v[i].w * sc; }
.LBB0_472:
	s_waitcnt vmcnt(0)
	v_pk_mul_f32 v[34:35], v[34:35], v[0:1] op_sel_hi:[1,0]
	v_add_u32_e32 v38, v69, v107
	ds_write2_b32 v38, v34, v35 offset1:1
	v_pk_mul_f32 v[34:35], v[36:37], v[0:1] op_sel_hi:[1,0]
	ds_write2_b32 v38, v34, v35 offset0:2 offset1:3
	s_and_b64 vcc, exec, s[40:41]
	v_add_u32_e32 v34, v69, v108
	s_cbranch_vccnz .LBB0_487
	v_lshl_add_u64 v[36:37], v[88:89], 0, v[70:71]
	v_lshl_add_u64 v[36:37], v[36:37], 2, s[46:47]
	v_mov_b32_e32 v0, v225
	s_waitcnt vmcnt(0)
	v_pk_mul_f32 v[38:39], v[30:31], v[0:1] op_sel_hi:[1,0]
	ds_write2_b32 v34, v38, v39 offset1:1
	v_pk_mul_f32 v[38:39], v[32:33], v[0:1] op_sel_hi:[1,0]
	v_mov_b32_e32 v0, v226
	ds_write2_b32 v34, v38, v39 offset0:2 offset1:3
	s_cbranch_execnz .LBB0_475

; DI void tr_item(const float* W, int N, const float* scale, bf16_t* WT, int ldk, int koff, int gu, int which, float* scr, int item, int lane) {
;     ...
;     for (int i = 0; i < 16; ++i) { const int kk = 4 * i + lr; const float sc = scale ? scale[k0 + kk] : 1.f; float* d = scr + kk * 65 + lc;
;         d[0] = v[i].x * sc; d[1] = v[i].y * sc; d[2] = v[i].z * sc; d[3] = v[i].w * sc; }
.LBB0_475:
	s_waitcnt vmcnt(0)
	v_pk_mul_f32 v[26:27], v[26:27], v[0:1] op_sel_hi:[1,0]
	v_add_u32_e32 v30, v69, v109
	ds_write2_b32 v30, v26, v27 offset1:1
	v_pk_mul_f32 v[26:27], v[28:29], v[0:1] op_sel_hi:[1,0]
	ds_write2_b32 v30, v26, v27 offset0:2 offset1:3
	s_and_b64 vcc, exec, s[40:41]
	v_add_u32_e32 v26, v69, v110
	s_cbranch_vccnz .LBB0_488
	v_lshl_add_u64 v[28:29], v[88:89], 0, v[70:71]
	v_lshl_add_u64 v[28:29], v[28:29], 2, s[46:47]
	v_mov_b32_e32 v0, v227
	s_waitcnt vmcnt(0)
	v_pk_mul_f32 v[30:31], v[22:23], v[0:1] op_sel_hi:[1,0]
	ds_write2_b32 v26, v30, v31 offset1:1
	v_pk_mul_f32 v[30:31], v[24:25], v[0:1] op_sel_hi:[1,0]
	v_mov_b32_e32 v0, v228
	ds_write2_b32 v26, v30, v31 offset0:2 offset1:3
	s_cbranch_execnz .LBB0_478

; DI void tr_item(const float* W, int N, const float* scale, bf16_t* WT, int ldk, int koff, int gu, int which, float* scr, int item, int lane) {
;     ...
;     for (int i = 0; i < 16; ++i) { const int kk = 4 * i + lr; const float sc = scale ? scale[k0 + kk] : 1.f; float* d = scr + kk * 65 + lc;
;         d[0] = v[i].x * sc; d[1] = v[i].y * sc; d[2] = v[i].z * sc; d[3] = v[i].w * sc; }
.LBB0_478:
	s_waitcnt vmcnt(0)
	v_pk_mul_f32 v[22:23], v[18:19], v[0:1] op_sel_hi:[1,0]
	v_add_u32_e32 v18, v69, v111
	v_pk_mul_f32 v[20:21], v[20:21], v[0:1] op_sel_hi:[1,0]
	ds_write2_b32 v18, v20, v21 offset0:2 offset1:3
	s_and_b64 vcc, exec, s[40:41]
	v_add_u32_e32 v19, 0x410, v18
	v_add_u32_e32 v20, 0x418, v18
	ds_write2_b32 v18, v22, v23 offset1:1
	s_cbranch_vccnz .LBB0_489
	v_lshl_add_u64 v[22:23], v[88:89], 0, v[70:71]
	v_lshl_add_u64 v[22:23], v[22:23], 2, s[46:47]
	v_mov_b32_e32 v0, v229
	s_waitcnt vmcnt(0)
	v_pk_mul_f32 v[24:25], v[14:15], v[0:1] op_sel_hi:[1,0]
	ds_write2_b32 v19, v24, v25 offset1:1
	v_pk_mul_f32 v[24:25], v[16:17], v[0:1] op_sel_hi:[1,0]
	v_mov_b32_e32 v0, v230
	ds_write2_b32 v20, v24, v25 offset1:1
	s_cbranch_execnz .LBB0_481

; DI void tr_item(const float* W, int N, const float* scale, bf16_t* WT, int ldk, int koff, int gu, int which, float* scr, int item, int lane) {
;     ...
;     for (int i = 0; i < 16; ++i) { const int kk = 4 * i + lr; const float sc = scale ? scale[k0 + kk] : 1.f; float* d = scr + kk * 65 + lc;
;         d[0] = v[i].x * sc; d[1] = v[i].y * sc; d[2] = v[i].z * sc; d[3] = v[i].w * sc; }
.LBB0_481:
	s_waitcnt vmcnt(0)
	v_pk_mul_f32 v[10:11], v[10:11], v[0:1] op_sel_hi:[1,0]
	v_add_u32_e32 v14, 0x820, v18
	ds_write2_b32 v14, v10, v11 offset1:1
	v_pk_mul_f32 v[10:11], v[12:13], v[0:1] op_sel_hi:[1,0]
	v_add_u32_e32 v0, 0x828, v18
	ds_write2_b32 v0, v10, v11 offset1:1
	s_and_b64 vcc, exec, s[40:41]
	v_add_u32_e32 v10, 0xc30, v18
	v_add_u32_e32 v11, 0xc38, v18
	s_cbranch_vccnz .LBB0_490
	v_lshl_add_u64 v[12:13], v[88:89], 0, v[70:71]
	v_lshl_add_u64 v[12:13], v[12:13], 2, s[46:47]
	v_mov_b32_e32 v0, v231
	s_waitcnt vmcnt(0)
	v_pk_mul_f32 v[14:15], v[6:7], v[0:1] op_sel_hi:[1,0]
	ds_write2_b32 v10, v14, v15 offset1:1
	v_pk_mul_f32 v[14:15], v[8:9], v[0:1] op_sel_hi:[1,0]
	v_mov_b32_e32 v0, v232
	ds_write2_b32 v11, v14, v15 offset1:1
	s_cbranch_execnz .LBB0_383
	s_branch .LBB0_382
